# attention K Q^T: 16 K-fragment LDS reads issued up front, counted waits before each MFMA
# speedup vs baseline: 1.0012x; 1.0009x over previous
.LBB0_1184:
	s_or_b64 exec, exec, s[18:19]
	v_cndmask_b32_e64 v1, 0, v121, s[0:1]
	v_cndmask_b32_e32 v1, v1, v119, vcc
	v_cndmask_b32_e64 v1, v1, v120, s[4:5]
	v_cmp_eq_u32_e32 vcc, 1, v1
	v_mov_b32_e32 v2, 0xfffffc18
	v_mov_b32_e32 v3, 0x3e8
	v_cndmask_b32_e64 v2, v2, 0, vcc
	v_cmp_eq_u32_e32 vcc, 2, v1
	v_cmp_ne_u32_e64 s[0:1], 0, v1
	s_nop 0
	v_cndmask_b32_e64 v3, v3, 0, vcc
	ds_read_b128 v[92:95], v202
	ds_read_b128 v[216:219], v202 offset:64
	ds_read_b128 v[84:87], v202 offset:2304
	ds_read_b128 v[220:223], v202 offset:2368
	ds_read_b128 v[88:91], v202 offset:4608
	ds_read_b128 v[226:229], v202 offset:4672
	ds_read_b128 v[80:83], v202 offset:6912
	ds_read_b128 v[236:239], v202 offset:6976
	ds_read_b128 v[76:79], v202 offset:9216
	ds_read_b128 v[240:243], v202 offset:9280
	ds_read_b128 v[72:75], v202 offset:11520
	ds_read_b128 v[244:247], v202 offset:11584
	ds_read_b128 v[68:71], v202 offset:13824
	ds_read_b128 v[248:251], v202 offset:13888
	ds_read_b128 v[96:99], v202 offset:16128
	ds_read_b128 v[208:211], v202 offset:16192
	s_waitcnt lgkmcnt(15)
	v_mfma_f32_16x16x32_bf16 v[92:95], v[92:95], v[4:7], 0
	s_waitcnt lgkmcnt(14)
	v_mfma_f32_16x16x32_bf16 v[92:95], v[216:219], v[8:11], v[92:95]
	s_waitcnt lgkmcnt(13)
	v_mfma_f32_16x16x32_bf16 v[84:87], v[84:87], v[4:7], 0
	s_waitcnt lgkmcnt(12)
	v_mfma_f32_16x16x32_bf16 v[84:87], v[220:223], v[8:11], v[84:87]
	s_waitcnt lgkmcnt(11)
	v_mfma_f32_16x16x32_bf16 v[88:91], v[88:91], v[4:7], 0
	s_waitcnt lgkmcnt(10)
	v_mfma_f32_16x16x32_bf16 v[88:91], v[226:229], v[8:11], v[88:91]
	s_waitcnt lgkmcnt(9)
	v_mfma_f32_16x16x32_bf16 v[80:83], v[80:83], v[4:7], 0
	s_waitcnt lgkmcnt(8)
	v_mfma_f32_16x16x32_bf16 v[80:83], v[236:239], v[8:11], v[80:83]
	s_waitcnt lgkmcnt(7)
	v_mfma_f32_16x16x32_bf16 v[76:79], v[76:79], v[4:7], 0
	s_waitcnt lgkmcnt(6)
	v_mfma_f32_16x16x32_bf16 v[76:79], v[240:243], v[8:11], v[76:79]
	s_waitcnt lgkmcnt(5)
	v_mfma_f32_16x16x32_bf16 v[72:75], v[72:75], v[4:7], 0
	s_waitcnt lgkmcnt(4)
	v_mfma_f32_16x16x32_bf16 v[72:75], v[244:247], v[8:11], v[72:75]
	s_waitcnt lgkmcnt(3)
	v_mfma_f32_16x16x32_bf16 v[68:71], v[68:71], v[4:7], 0
	s_waitcnt lgkmcnt(2)
	v_mfma_f32_16x16x32_bf16 v[68:71], v[248:251], v[8:11], v[68:71]
	s_waitcnt lgkmcnt(1)
	v_mfma_f32_16x16x32_bf16 v[96:99], v[96:99], v[4:7], 0
	s_waitcnt lgkmcnt(0)
	v_mfma_f32_16x16x32_bf16 v[96:99], v[208:211], v[8:11], v[96:99]
	s_and_saveexec_b64 s[6:7], s[0:1]
	s_cbranch_execz .LBB0_1186
	v_cmp_lt_i32_e32 vcc, v130, v2
	v_cmp_gt_i32_e64 s[4:5], v130, v3
	s_or_b64 vcc, vcc, s[4:5]
	v_cndmask_b32_e32 v92, v92, v233, vcc
	v_cmp_lt_i32_e32 vcc, v131, v2
	v_cmp_ge_i32_e64 s[4:5], v130, v3
	s_or_b64 vcc, vcc, s[4:5]
	v_cndmask_b32_e32 v93, v93, v233, vcc
	v_cmp_lt_i32_e32 vcc, v132, v2
	v_cmp_gt_i32_e64 s[4:5], v132, v3
	s_or_b64 vcc, vcc, s[4:5]
	v_cndmask_b32_e32 v94, v94, v233, vcc
	v_cmp_lt_i32_e32 vcc, v133, v2
	v_cmp_gt_i32_e64 s[4:5], v133, v3
	s_or_b64 vcc, vcc, s[4:5]
	v_cndmask_b32_e32 v95, v95, v233, vcc
	v_cmp_lt_i32_e32 vcc, v134, v2
	v_cmp_gt_i32_e64 s[4:5], v134, v3
	s_or_b64 vcc, vcc, s[4:5]
	v_cndmask_b32_e32 v84, v84, v233, vcc
	v_cmp_lt_i32_e32 vcc, v135, v2
	v_cmp_gt_i32_e64 s[4:5], v135, v3
	s_or_b64 vcc, vcc, s[4:5]
	v_cndmask_b32_e32 v85, v85, v233, vcc
	v_cmp_lt_i32_e32 vcc, v136, v2
	v_cmp_gt_i32_e64 s[4:5], v136, v3
	s_or_b64 vcc, vcc, s[4:5]
	v_cndmask_b32_e32 v86, v86, v233, vcc
	v_cmp_lt_i32_e32 vcc, v137, v2
	v_cmp_gt_i32_e64 s[4:5], v137, v3
	s_or_b64 vcc, vcc, s[4:5]
	v_cndmask_b32_e32 v87, v87, v233, vcc
	v_cmp_lt_i32_e32 vcc, v138, v2
	v_cmp_gt_i32_e64 s[4:5], v138, v3
	s_or_b64 vcc, vcc, s[4:5]
	v_cndmask_b32_e32 v88, v88, v233, vcc
	v_cmp_lt_i32_e32 vcc, v139, v2
	v_cmp_gt_i32_e64 s[4:5], v139, v3
	s_or_b64 vcc, vcc, s[4:5]
	v_cndmask_b32_e32 v89, v89, v233, vcc
	v_cmp_lt_i32_e32 vcc, v140, v2
	v_cmp_gt_i32_e64 s[4:5], v140, v3
	s_or_b64 vcc, vcc, s[4:5]
	v_cndmask_b32_e32 v90, v90, v233, vcc
	v_cmp_lt_i32_e32 vcc, v141, v2
	v_cmp_gt_i32_e64 s[4:5], v141, v3
	s_or_b64 vcc, vcc, s[4:5]
	v_cndmask_b32_e32 v91, v91, v233, vcc
	v_cmp_lt_i32_e32 vcc, v142, v2
	v_cmp_gt_i32_e64 s[4:5], v142, v3
	s_or_b64 vcc, vcc, s[4:5]
	v_cndmask_b32_e32 v80, v80, v233, vcc
	v_cmp_lt_i32_e32 vcc, v143, v2
	v_cmp_gt_i32_e64 s[4:5], v143, v3
	s_or_b64 vcc, vcc, s[4:5]
	v_cndmask_b32_e32 v81, v81, v233, vcc
	v_cmp_lt_i32_e32 vcc, v144, v2
	v_cmp_gt_i32_e64 s[4:5], v144, v3
	s_or_b64 vcc, vcc, s[4:5]
	v_cndmask_b32_e32 v82, v82, v233, vcc
	v_cmp_lt_i32_e32 vcc, v145, v2
	v_cmp_gt_i32_e64 s[4:5], v145, v3
	s_or_b64 vcc, vcc, s[4:5]
	v_cndmask_b32_e32 v83, v83, v233, vcc
	v_cmp_lt_i32_e32 vcc, v148, v2
	v_cmp_gt_i32_e64 s[4:5], v148, v3
	s_or_b64 vcc, vcc, s[4:5]
	v_cndmask_b32_e32 v76, v76, v233, vcc
	v_cmp_lt_i32_e32 vcc, v149, v2
	v_cmp_gt_i32_e64 s[4:5], v149, v3
	s_or_b64 vcc, vcc, s[4:5]
	v_cndmask_b32_e32 v77, v77, v233, vcc
	v_cmp_lt_i32_e32 vcc, v150, v2
	v_cmp_gt_i32_e64 s[4:5], v150, v3
	s_or_b64 vcc, vcc, s[4:5]
	v_cndmask_b32_e32 v78, v78, v233, vcc
	v_cmp_lt_i32_e32 vcc, v151, v2
	v_cmp_gt_i32_e64 s[4:5], v151, v3
	s_or_b64 vcc, vcc, s[4:5]
	v_cndmask_b32_e32 v79, v79, v233, vcc
	v_cmp_lt_i32_e32 vcc, v152, v2
	v_cmp_gt_i32_e64 s[4:5], v152, v3
	s_or_b64 vcc, vcc, s[4:5]
	v_cndmask_b32_e32 v72, v72, v233, vcc
	v_cmp_lt_i32_e32 vcc, v153, v2
	v_cmp_gt_i32_e64 s[4:5], v153, v3
	s_or_b64 vcc, vcc, s[4:5]
	v_cndmask_b32_e32 v73, v73, v233, vcc
	v_cmp_lt_i32_e32 vcc, v154, v2
	v_cmp_gt_i32_e64 s[4:5], v154, v3
	s_or_b64 vcc, vcc, s[4:5]
	v_cndmask_b32_e32 v74, v74, v233, vcc
	v_cmp_lt_i32_e32 vcc, v155, v2
	v_cmp_gt_i32_e64 s[4:5], v155, v3
	s_or_b64 vcc, vcc, s[4:5]
	v_cndmask_b32_e32 v75, v75, v233, vcc
	v_cmp_lt_i32_e32 vcc, v156, v2
	v_cmp_gt_i32_e64 s[4:5], v156, v3
	s_or_b64 vcc, vcc, s[4:5]
	v_cndmask_b32_e32 v68, v68, v233, vcc
	v_cmp_lt_i32_e32 vcc, v157, v2
	v_cmp_gt_i32_e64 s[4:5], v157, v3
	s_or_b64 vcc, vcc, s[4:5]
	v_cndmask_b32_e32 v69, v69, v233, vcc
	v_cmp_lt_i32_e32 vcc, v158, v2
	v_cmp_gt_i32_e64 s[4:5], v158, v3
	s_or_b64 vcc, vcc, s[4:5]
	v_cndmask_b32_e32 v70, v70, v233, vcc
	v_cmp_lt_i32_e32 vcc, v159, v2
	v_cmp_gt_i32_e64 s[4:5], v159, v3
	s_or_b64 vcc, vcc, s[4:5]
	v_cndmask_b32_e32 v71, v71, v233, vcc
	v_cmp_lt_i32_e32 vcc, v160, v2
	v_cmp_gt_i32_e64 s[4:5], v160, v3
	s_or_b64 vcc, vcc, s[4:5]
	v_cndmask_b32_e32 v96, v96, v233, vcc
	v_cmp_lt_i32_e32 vcc, v161, v2
	v_cmp_gt_i32_e64 s[4:5], v161, v3
	s_or_b64 vcc, vcc, s[4:5]
	v_cndmask_b32_e32 v97, v97, v233, vcc
	v_cmp_lt_i32_e32 vcc, v162, v2
	v_cmp_gt_i32_e64 s[4:5], v162, v3
	s_or_b64 vcc, vcc, s[4:5]
	v_cndmask_b32_e32 v98, v98, v233, vcc
	v_cmp_lt_i32_e32 vcc, v163, v2
	v_cmp_gt_i32_e64 s[4:5], v163, v3
	s_or_b64 vcc, vcc, s[4:5]
	v_cndmask_b32_e32 v99, v99, v233, vcc

.LBB0_1188:
	v_cvt_pk_bf16_f32 v92, v92, v93
	v_cvt_pk_bf16_f32 v93, v94, v95
	v_cvt_pk_bf16_f32 v94, v207, v208
	v_add_u32_e32 v208, 0x4800, v203
	ds_read2_b64 v[96:99], v208 offset1:4
	v_cvt_pk_bf16_f32 v84, v84, v85
	v_cvt_pk_bf16_f32 v85, v86, v87
	v_cvt_pk_bf16_f32 v86, v88, v89
	v_cvt_pk_bf16_f32 v87, v90, v91
	ds_read2_b64 v[88:91], v208 offset0:8 offset1:12
	v_cvt_pk_bf16_f32 v95, v209, v212
	v_add_u32_e32 v206, 0x4800, v204
	v_cvt_pk_bf16_f32 v76, v76, v77
	v_cvt_pk_bf16_f32 v77, v78, v79
	v_cvt_pk_bf16_f32 v78, v80, v81
	v_cvt_pk_bf16_f32 v79, v82, v83
	ds_read2_b64 v[80:83], v208 offset0:16 offset1:20
	s_waitcnt lgkmcnt(2)
	v_mfma_f32_16x16x32_bf16 v[64:67], v[96:99], v[92:95], v[64:67]
	ds_read2_b64 v[96:99], v206 offset1:4
	v_cvt_pk_bf16_f32 v68, v68, v69
	v_cvt_pk_bf16_f32 v69, v70, v71
	v_cvt_pk_bf16_f32 v70, v72, v73
	v_cvt_pk_bf16_f32 v71, v74, v75
	ds_read2_b64 v[72:75], v208 offset0:24 offset1:28
	s_waitcnt lgkmcnt(3)
	v_mfma_f32_16x16x32_bf16 v[64:67], v[88:91], v[84:87], v[64:67]
	ds_read2_b64 v[88:91], v206 offset0:8 offset1:12
	v_add_u32_e32 v207, 0x5800, v204
	v_add_u32_e32 v209, 0x6800, v204
	s_waitcnt lgkmcnt(3)
	v_mfma_f32_16x16x32_bf16 v[64:67], v[80:83], v[76:79], v[64:67]
	ds_read2_b64 v[80:83], v206 offset0:16 offset1:20
	s_waitcnt lgkmcnt(3)
	v_mfma_f32_16x16x32_bf16 v[60:63], v[96:99], v[92:95], v[60:63]
	ds_read2_b64 v[96:99], v207 offset0:32 offset1:36
	s_waitcnt lgkmcnt(3)
	v_mfma_f32_16x16x32_bf16 v[64:67], v[72:75], v[68:71], v[64:67]
	ds_read2_b64 v[72:75], v206 offset0:24 offset1:28
	s_waitcnt lgkmcnt(3)
	v_mfma_f32_16x16x32_bf16 v[60:63], v[88:91], v[84:87], v[60:63]
	ds_read2_b64 v[88:91], v207 offset0:40 offset1:44
	s_waitcnt lgkmcnt(3)
	v_mfma_f32_16x16x32_bf16 v[60:63], v[80:83], v[76:79], v[60:63]
	ds_read2_b64 v[80:83], v207 offset0:48 offset1:52
	s_waitcnt lgkmcnt(3)
	v_mfma_f32_16x16x32_bf16 v[56:59], v[96:99], v[92:95], v[56:59]
	ds_read2_b64 v[96:99], v209 offset0:64 offset1:68
	s_waitcnt lgkmcnt(3)
	v_mfma_f32_16x16x32_bf16 v[60:63], v[72:75], v[68:71], v[60:63]
	ds_read2_b64 v[72:75], v207 offset0:56 offset1:60
	s_waitcnt lgkmcnt(3)
	v_mfma_f32_16x16x32_bf16 v[56:59], v[88:91], v[84:87], v[56:59]
	ds_read2_b64 v[88:91], v209 offset0:72 offset1:76
	s_waitcnt lgkmcnt(3)
	v_mfma_f32_16x16x32_bf16 v[56:59], v[80:83], v[76:79], v[56:59]
	ds_read2_b64 v[80:83], v209 offset0:80 offset1:84
	s_waitcnt lgkmcnt(3)
	v_mfma_f32_16x16x32_bf16 v[52:55], v[96:99], v[92:95], v[52:55]
	s_waitcnt lgkmcnt(2)
	v_mfma_f32_16x16x32_bf16 v[56:59], v[72:75], v[68:71], v[56:59]
	ds_read2_b64 v[72:75], v209 offset0:88 offset1:92
	s_waitcnt lgkmcnt(2)
	v_mfma_f32_16x16x32_bf16 v[52:55], v[88:91], v[84:87], v[52:55]
	s_waitcnt lgkmcnt(1)
	v_mfma_f32_16x16x32_bf16 v[52:55], v[80:83], v[76:79], v[52:55]
	s_waitcnt lgkmcnt(0)
	v_mfma_f32_16x16x32_bf16 v[52:55], v[72:75], v[68:71], v[52:55]
	ds_read_b128 v[96:99], v202
	ds_read_b128 v[216:219], v202 offset:64
	ds_read_b128 v[92:95], v202 offset:2304
	ds_read_b128 v[220:223], v202 offset:2368
	ds_read_b128 v[88:91], v202 offset:4608
	ds_read_b128 v[226:229], v202 offset:4672
	ds_read_b128 v[84:87], v202 offset:6912
	ds_read_b128 v[236:239], v202 offset:6976
	ds_read_b128 v[80:83], v202 offset:9216
	ds_read_b128 v[240:243], v202 offset:9280
	ds_read_b128 v[76:79], v202 offset:11520
	ds_read_b128 v[244:247], v202 offset:11584
	ds_read_b128 v[72:75], v202 offset:13824
	ds_read_b128 v[248:251], v202 offset:13888
	ds_read_b128 v[68:71], v202 offset:16128
	ds_read_b128 v[212:215], v202 offset:16192
	s_waitcnt lgkmcnt(15)
	v_mfma_f32_16x16x32_bf16 v[96:99], v[96:99], v[12:15], 0
	s_waitcnt lgkmcnt(14)
	v_mfma_f32_16x16x32_bf16 v[96:99], v[216:219], v[16:19], v[96:99]
	s_waitcnt lgkmcnt(13)
	v_mfma_f32_16x16x32_bf16 v[92:95], v[92:95], v[12:15], 0
	s_waitcnt lgkmcnt(12)
	v_mfma_f32_16x16x32_bf16 v[92:95], v[220:223], v[16:19], v[92:95]
	s_waitcnt lgkmcnt(11)
	v_mfma_f32_16x16x32_bf16 v[88:91], v[88:91], v[12:15], 0
	s_waitcnt lgkmcnt(10)
	v_mfma_f32_16x16x32_bf16 v[88:91], v[226:229], v[16:19], v[88:91]
	s_waitcnt lgkmcnt(9)
	v_mfma_f32_16x16x32_bf16 v[84:87], v[84:87], v[12:15], 0
	s_waitcnt lgkmcnt(8)
	v_mfma_f32_16x16x32_bf16 v[84:87], v[236:239], v[16:19], v[84:87]
	s_waitcnt lgkmcnt(7)
	v_mfma_f32_16x16x32_bf16 v[80:83], v[80:83], v[12:15], 0
	s_waitcnt lgkmcnt(6)
	v_mfma_f32_16x16x32_bf16 v[80:83], v[240:243], v[16:19], v[80:83]
	s_waitcnt lgkmcnt(5)
	v_mfma_f32_16x16x32_bf16 v[76:79], v[76:79], v[12:15], 0
	s_waitcnt lgkmcnt(4)
	v_mfma_f32_16x16x32_bf16 v[76:79], v[244:247], v[16:19], v[76:79]
	s_waitcnt lgkmcnt(3)
	v_mfma_f32_16x16x32_bf16 v[72:75], v[72:75], v[12:15], 0
	s_waitcnt lgkmcnt(2)
	v_mfma_f32_16x16x32_bf16 v[72:75], v[248:251], v[16:19], v[72:75]
	s_waitcnt lgkmcnt(1)
	v_mfma_f32_16x16x32_bf16 v[68:71], v[68:71], v[12:15], 0
	s_waitcnt lgkmcnt(0)
	v_mfma_f32_16x16x32_bf16 v[68:71], v[212:215], v[16:19], v[68:71]
	s_and_saveexec_b64 s[4:5], s[0:1]
	s_cbranch_execz .LBB0_1190
	v_cmp_lt_i32_e32 vcc, v164, v2
	v_cmp_gt_i32_e64 s[0:1], v164, v3
	s_or_b64 vcc, vcc, s[0:1]
	v_cndmask_b32_e32 v96, v96, v233, vcc
	v_cmp_lt_i32_e32 vcc, v165, v2
	v_cmp_ge_i32_e64 s[0:1], v164, v3
	s_or_b64 vcc, vcc, s[0:1]
	v_cndmask_b32_e32 v97, v97, v233, vcc
	v_cmp_lt_i32_e32 vcc, v166, v2
	v_cmp_gt_i32_e64 s[0:1], v166, v3
	s_or_b64 vcc, vcc, s[0:1]
	v_cndmask_b32_e32 v98, v98, v233, vcc
	v_cmp_lt_i32_e32 vcc, v167, v2
	v_cmp_gt_i32_e64 s[0:1], v167, v3
	s_or_b64 vcc, vcc, s[0:1]
	v_cndmask_b32_e32 v99, v99, v233, vcc
	v_cmp_lt_i32_e32 vcc, v168, v2
	v_cmp_gt_i32_e64 s[0:1], v168, v3
	s_or_b64 vcc, vcc, s[0:1]
	v_cndmask_b32_e32 v92, v92, v233, vcc
	v_cmp_lt_i32_e32 vcc, v169, v2
	v_cmp_gt_i32_e64 s[0:1], v169, v3
	s_or_b64 vcc, vcc, s[0:1]
	v_cndmask_b32_e32 v93, v93, v233, vcc
	v_cmp_lt_i32_e32 vcc, v170, v2
	v_cmp_gt_i32_e64 s[0:1], v170, v3
	s_or_b64 vcc, vcc, s[0:1]
	v_cndmask_b32_e32 v94, v94, v233, vcc
	v_cmp_lt_i32_e32 vcc, v171, v2
	v_cmp_gt_i32_e64 s[0:1], v171, v3
	s_or_b64 vcc, vcc, s[0:1]
	v_cndmask_b32_e32 v95, v95, v233, vcc
	v_cmp_lt_i32_e32 vcc, v172, v2
	v_cmp_gt_i32_e64 s[0:1], v172, v3
	s_or_b64 vcc, vcc, s[0:1]
	v_cndmask_b32_e32 v88, v88, v233, vcc
	v_cmp_lt_i32_e32 vcc, v173, v2
	v_cmp_gt_i32_e64 s[0:1], v173, v3
	s_or_b64 vcc, vcc, s[0:1]
	v_cndmask_b32_e32 v89, v89, v233, vcc
	v_cmp_lt_i32_e32 vcc, v174, v2
	v_cmp_gt_i32_e64 s[0:1], v174, v3
	s_or_b64 vcc, vcc, s[0:1]
	v_cndmask_b32_e32 v90, v90, v233, vcc
	v_cmp_lt_i32_e32 vcc, v175, v2
	v_cmp_gt_i32_e64 s[0:1], v175, v3
	s_or_b64 vcc, vcc, s[0:1]
	v_cndmask_b32_e32 v91, v91, v233, vcc
	v_cmp_lt_i32_e32 vcc, v176, v2
	v_cmp_gt_i32_e64 s[0:1], v176, v3
	s_or_b64 vcc, vcc, s[0:1]
	v_cndmask_b32_e32 v84, v84, v233, vcc
	v_cmp_lt_i32_e32 vcc, v177, v2
	v_cmp_gt_i32_e64 s[0:1], v177, v3
	s_or_b64 vcc, vcc, s[0:1]
	v_cndmask_b32_e32 v85, v85, v233, vcc
	v_cmp_lt_i32_e32 vcc, v178, v2
	v_cmp_gt_i32_e64 s[0:1], v178, v3
	s_or_b64 vcc, vcc, s[0:1]
	v_cndmask_b32_e32 v86, v86, v233, vcc
	v_cmp_lt_i32_e32 vcc, v179, v2
	v_cmp_gt_i32_e64 s[0:1], v179, v3
	s_or_b64 vcc, vcc, s[0:1]
	v_cndmask_b32_e32 v87, v87, v233, vcc
	v_cmp_lt_i32_e32 vcc, v180, v2
	v_cmp_gt_i32_e64 s[0:1], v180, v3
	s_or_b64 vcc, vcc, s[0:1]
	v_cndmask_b32_e32 v80, v80, v233, vcc
	v_cmp_lt_i32_e32 vcc, v181, v2
	v_cmp_gt_i32_e64 s[0:1], v181, v3
	s_or_b64 vcc, vcc, s[0:1]
	v_cndmask_b32_e32 v81, v81, v233, vcc
	v_cmp_lt_i32_e32 vcc, v182, v2
	v_cmp_gt_i32_e64 s[0:1], v182, v3
	s_or_b64 vcc, vcc, s[0:1]
	v_cndmask_b32_e32 v82, v82, v233, vcc
	v_cmp_lt_i32_e32 vcc, v183, v2
	v_cmp_gt_i32_e64 s[0:1], v183, v3
	s_or_b64 vcc, vcc, s[0:1]
	v_cndmask_b32_e32 v83, v83, v233, vcc
	v_cmp_lt_i32_e32 vcc, v184, v2
	v_cmp_gt_i32_e64 s[0:1], v184, v3
	s_or_b64 vcc, vcc, s[0:1]
	v_cndmask_b32_e32 v76, v76, v233, vcc
	v_cmp_lt_i32_e32 vcc, v185, v2
	v_cmp_gt_i32_e64 s[0:1], v185, v3
	s_or_b64 vcc, vcc, s[0:1]
	v_cndmask_b32_e32 v77, v77, v233, vcc
	v_cmp_lt_i32_e32 vcc, v186, v2
	v_cmp_gt_i32_e64 s[0:1], v186, v3
	s_or_b64 vcc, vcc, s[0:1]
	v_cndmask_b32_e32 v78, v78, v233, vcc
	v_cmp_lt_i32_e32 vcc, v187, v2
	v_cmp_gt_i32_e64 s[0:1], v187, v3
	s_or_b64 vcc, vcc, s[0:1]
	v_cndmask_b32_e32 v79, v79, v233, vcc
	v_cmp_lt_i32_e32 vcc, v188, v2
	v_cmp_gt_i32_e64 s[0:1], v188, v3
	s_or_b64 vcc, vcc, s[0:1]
	v_cndmask_b32_e32 v72, v72, v233, vcc
	v_cmp_lt_i32_e32 vcc, v189, v2
	v_cmp_gt_i32_e64 s[0:1], v189, v3
	s_or_b64 vcc, vcc, s[0:1]
	v_cndmask_b32_e32 v73, v73, v233, vcc
	v_cmp_lt_i32_e32 vcc, v190, v2
	v_cmp_gt_i32_e64 s[0:1], v190, v3
	s_or_b64 vcc, vcc, s[0:1]
	v_cndmask_b32_e32 v74, v74, v233, vcc
	v_cmp_lt_i32_e32 vcc, v191, v2
	v_cmp_gt_i32_e64 s[0:1], v191, v3
	s_or_b64 vcc, vcc, s[0:1]
	v_cndmask_b32_e32 v75, v75, v233, vcc
	v_cmp_lt_i32_e32 vcc, v192, v2
	v_cmp_gt_i32_e64 s[0:1], v192, v3
	s_or_b64 vcc, vcc, s[0:1]
	v_cndmask_b32_e32 v68, v68, v233, vcc
	v_cmp_lt_i32_e32 vcc, v193, v2
	v_cmp_gt_i32_e64 s[0:1], v193, v3
	s_or_b64 vcc, vcc, s[0:1]
	v_cndmask_b32_e32 v69, v69, v233, vcc
	v_cmp_lt_i32_e32 vcc, v194, v2
	v_cmp_gt_i32_e64 s[0:1], v194, v3
	s_or_b64 vcc, vcc, s[0:1]
	v_cndmask_b32_e32 v70, v70, v233, vcc
	v_cmp_lt_i32_e32 vcc, v195, v2
	v_cmp_gt_i32_e64 s[0:1], v195, v3
	s_or_b64 vcc, vcc, s[0:1]
	v_cndmask_b32_e32 v71, v71, v233, vcc
